# first 1375 w_up tiles transposed by the 55 in-proj workgroups that only have 6 GEMM units (after they finish)
# baseline (speedup 1.0000x reference)
.LBB0_568:
	s_cmpk_lt_i32 s2, 0xb9
	s_cbranch_scc1 .Lwi_exit
	s_cmpk_lt_i32 s2, 0xf0
	s_cbranch_scc0 .Lwi_exit
	s_load_dwordx2 s[18:19], s[0:1], 0x68
	s_load_dwordx2 s[20:21], s[0:1], 0x60
	s_load_dwordx2 s[22:23], s[0:1], 0x80
	s_mov_b64 exec, -1
	s_sub_i32 s24, s2, 0xb9
	s_addk_i32 s24, 0x840
	v_lshrrev_b32_e32 v40, 5, v156
	v_and_b32_e32 v41, 31, v156
	v_lshlrev_b32_e32 v41, 4, v41
	v_mul_u32_u24_e32 v42, 0x204, v40
	v_add_u32_e32 v42, v42, v41
	v_and_b32_e32 v43, 7, v156
	v_mul_u32_u24_e32 v43, 0x1020, v43
	v_lshrrev_b32_e32 v51, 3, v156
	v_lshl_add_u32 v43, v51, 2, v43
	v_lshrrev_b32_e32 v44, 4, v51
	v_lshlrev_b32_e32 v44, 1, v44
	v_bfe_u32 v52, v156, 2, 1
	v_add_u32_e32 v44, v44, v52
	v_lshlrev_b32_e32 v44, 10, v44
	v_and_b32_e32 v52, 15, v51
	v_lshlrev_b32_e32 v52, 6, v52
	v_and_b32_e32 v53, 3, v156
	v_lshl_add_u32 v52, v53, 4, v52
	v_and_b32_e32 v53, 8, v51
	v_lshlrev_b32_e32 v53, 2, v53
	v_xor_b32_e32 v52, v52, v53
	v_add_u32_e32 v44, v44, v52
	v_add_u32_e32 v45, 0x2000, v44
	v_lshlrev_b32_e32 v50, 2, v40
	s_waitcnt lgkmcnt(0)
	s_cmpk_lt_i32 s24, 0x1340
	s_cbranch_scc0 .Lwi_down_p
	s_sub_i32 s25, s24, 0x840
	s_and_b32 s26, s25, 31
	s_lshr_b32 s27, s25, 5
	s_lshl_b32 s28, s26, 6
	s_and_b32 s29, s27, 1
	s_mul_i32 s29, s29, 0x1600
	s_lshr_b32 s30, s27, 1
	s_lshl_b32 s30, s30, 7
	s_add_i32 s29, s29, s30
	s_mul_i32 s30, s28, 0x2c00
	s_add_i32 s30, s30, s29
	s_lshl_b32 s30, s30, 2
	s_add_u32 s34, s18, s30
	s_addc_u32 s35, s19, 0
	s_lshl_b32 s31, s27, 5
	s_add_i32 s31, s31, s26
	s_mov_b32 s33, 0xb000
	s_mov_b32 s46, 1
	s_mov_b32 s30, 0x2100000
	s_branch .Lwi_dec_p

.Lwi_dec_p:
	s_lshl_b32 s31, s31, 14
	s_add_u32 s31, s31, s30
	s_add_u32 s44, s40, s31
	s_addc_u32 s45, s41, 0
	v_mul_lo_u32 v46, v40, s33
	v_add_u32_e32 v46, v46, v41
	s_lshl_b32 s30, s33, 4
	v_add_u32_e32 v47, s30, v46
	v_add_u32_e32 v48, s30, v47
	v_add_u32_e32 v49, s30, v48
	global_load_dwordx4 v[0:3], v46, s[34:35]
	global_load_dwordx4 v[4:7], v47, s[34:35]
	global_load_dwordx4 v[8:11], v48, s[34:35]
	global_load_dwordx4 v[12:15], v49, s[34:35]
	s_and_b32 s30, s28, 0x7ff
	s_lshl_b32 s30, s30, 2
	s_add_u32 s34, s20, s30
	s_addc_u32 s35, s21, 0
	global_load_dword v16, v50, s[34:35]
	global_load_dword v17, v50, s[34:35] offset:64
	global_load_dword v18, v50, s[34:35] offset:128
	global_load_dword v19, v50, s[34:35] offset:192
	s_addk_i32 s24, 0x37
	s_cmpk_lt_i32 s24, 0x1340
	s_cbranch_scc0 .Lwi_down_q
	s_sub_i32 s25, s24, 0x840
	s_and_b32 s26, s25, 31
	s_lshr_b32 s27, s25, 5
	s_lshl_b32 s28, s26, 6
	s_and_b32 s29, s27, 1
	s_mul_i32 s29, s29, 0x1600
	s_lshr_b32 s30, s27, 1
	s_lshl_b32 s30, s30, 7
	s_add_i32 s29, s29, s30
	s_mul_i32 s30, s28, 0x2c00
	s_add_i32 s30, s30, s29
	s_lshl_b32 s30, s30, 2
	s_add_u32 s34, s18, s30
	s_addc_u32 s35, s19, 0
	s_lshl_b32 s31, s27, 5
	s_add_i32 s31, s31, s26
	s_mov_b32 s33, 0xb000
	s_mov_b32 s47, 1
	s_mov_b32 s30, 0x2100000
	s_branch .Lwi_dec_q

.Lwi_loop:
	s_addk_i32 s24, 0x37
	s_cmpk_lt_i32 s24, 0xd9f
	s_cbranch_scc0 .Lwi_lastB
	s_cmpk_lt_i32 s24, 0x1340
	s_cbranch_scc0 .Lwi_down_r
	s_sub_i32 s25, s24, 0x840
	s_and_b32 s26, s25, 31
	s_lshr_b32 s27, s25, 5
	s_lshl_b32 s28, s26, 6
	s_and_b32 s29, s27, 1
	s_mul_i32 s29, s29, 0x1600
	s_lshr_b32 s30, s27, 1
	s_lshl_b32 s30, s30, 7
	s_add_i32 s29, s29, s30
	s_mul_i32 s30, s28, 0x2c00
	s_add_i32 s30, s30, s29
	s_lshl_b32 s30, s30, 2
	s_add_u32 s34, s18, s30
	s_addc_u32 s35, s19, 0
	s_lshl_b32 s31, s27, 5
	s_add_i32 s31, s31, s26
	s_mov_b32 s33, 0xb000
	s_mov_b32 s46, 1
	s_mov_b32 s30, 0x2100000
	s_branch .Lwi_dec_r

.Lwi_nog_b1:
	ds_write_b32 v42, v20
	ds_write_b32 v42, v21 offset:4
	ds_write_b32 v42, v22 offset:8
	ds_write_b32 v42, v23 offset:12
	ds_write_b32 v42, v24 offset:8256
	ds_write_b32 v42, v25 offset:8260
	ds_write_b32 v42, v26 offset:8264
	ds_write_b32 v42, v27 offset:8268
	ds_write_b32 v42, v28 offset:16512
	ds_write_b32 v42, v29 offset:16516
	ds_write_b32 v42, v30 offset:16520
	ds_write_b32 v42, v31 offset:16524
	ds_write_b32 v42, v32 offset:24768
	ds_write_b32 v42, v33 offset:24772
	ds_write_b32 v42, v34 offset:24776
	ds_write_b32 v42, v35 offset:24780
	s_waitcnt lgkmcnt(0)
	s_barrier
	ds_read_b32 v54, v43
	ds_read_b32 v55, v43 offset:516
	ds_read_b32 v56, v43 offset:1032
	ds_read_b32 v57, v43 offset:1548
	ds_read_b32 v58, v43 offset:2064
	ds_read_b32 v59, v43 offset:2580
	ds_read_b32 v60, v43 offset:3096
	ds_read_b32 v61, v43 offset:3612
	ds_read_b32 v62, v43 offset:256
	ds_read_b32 v63, v43 offset:772
	ds_read_b32 v64, v43 offset:1288
	ds_read_b32 v65, v43 offset:1804
	ds_read_b32 v66, v43 offset:2320
	ds_read_b32 v67, v43 offset:2836
	ds_read_b32 v68, v43 offset:3352
	ds_read_b32 v69, v43 offset:3868
	s_waitcnt lgkmcnt(0)
	v_cvt_pk_bf16_f32 v72, v54, v55
	v_cvt_pk_bf16_f32 v73, v56, v57
	v_cvt_pk_bf16_f32 v74, v58, v59
	v_cvt_pk_bf16_f32 v75, v60, v61
	v_cvt_pk_bf16_f32 v76, v62, v63
	v_cvt_pk_bf16_f32 v77, v64, v65
	v_cvt_pk_bf16_f32 v78, v66, v67
	v_cvt_pk_bf16_f32 v79, v68, v69
	global_store_dwordx4 v44, v[72:75], s[48:49]
	global_store_dwordx4 v45, v[76:79], s[48:49]
	s_barrier
	s_addk_i32 s24, 0x37
	s_cmpk_lt_i32 s24, 0xd9f
	s_cbranch_scc0 .Lwi_lastA
	s_cmpk_lt_i32 s24, 0x1340
	s_cbranch_scc0 .Lwi_down_s
	s_sub_i32 s25, s24, 0x840
	s_and_b32 s26, s25, 31
	s_lshr_b32 s27, s25, 5
	s_lshl_b32 s28, s26, 6
	s_and_b32 s29, s27, 1
	s_mul_i32 s29, s29, 0x1600
	s_lshr_b32 s30, s27, 1
	s_lshl_b32 s30, s30, 7
	s_add_i32 s29, s29, s30
	s_mul_i32 s30, s28, 0x2c00
	s_add_i32 s30, s30, s29
	s_lshl_b32 s30, s30, 2
	s_add_u32 s34, s18, s30
	s_addc_u32 s35, s19, 0
	s_lshl_b32 s31, s27, 5
	s_add_i32 s31, s31, s26
	s_mov_b32 s33, 0xb000
	s_mov_b32 s47, 1
	s_mov_b32 s30, 0x2100000
	s_branch .Lwi_dec_s

.Lwi_done:
	s_branch .Lwi_exit
.Lwi_exit:
	s_and_saveexec_b64 s[4:5], s[36:37]
	s_cbranch_execz .LBB0_571
	s_mov_b64 s[6:7], exec
	v_mbcnt_lo_u32_b32 v0, s6, 0
	v_mbcnt_hi_u32_b32 v0, s7, v0
	v_cmp_eq_u32_e32 vcc, 0, v0
	s_and_b64 s[8:9], exec, vcc
	s_mov_b64 exec, s[8:9]
	s_cbranch_execz .LBB0_571
	s_bcnt1_i32_b64 s3, s[6:7]
	v_mov_b32_e32 v0, 0x6330000
	v_mov_b32_e32 v1, s3
	global_atomic_add v0, v1, s[40:41] offset:3204

.LBB0_1105:
	s_load_dword s3, s[0:1], 0xa8
	s_mov_b64 s[4:5], -1
	s_waitcnt lgkmcnt(0)
	s_addk_i32 s3, 0xffb0
	s_cmp_lt_i32 s2, s3
	s_cbranch_scc1 .LBB0_1127
	s_cmpk_lt_i32 s2, 0xf0
	s_cbranch_scc0 .Lwt_skip
	s_load_dwordx2 s[18:19], s[0:1], 0x68
	s_load_dwordx2 s[20:21], s[0:1], 0x60
	s_load_dwordx2 s[22:23], s[0:1], 0x80
	s_mov_b64 exec, -1
	s_sub_i32 s24, s2, 0xb0
	s_addk_i32 s24, 0xd9f
	v_lshrrev_b32_e32 v40, 5, v156
	v_and_b32_e32 v41, 31, v156
	v_lshlrev_b32_e32 v41, 4, v41
	v_mul_u32_u24_e32 v42, 0x204, v40
	v_add_u32_e32 v42, v42, v41
	v_and_b32_e32 v43, 7, v156
	v_mul_u32_u24_e32 v43, 0x1020, v43
	v_lshrrev_b32_e32 v51, 3, v156
	v_lshl_add_u32 v43, v51, 2, v43
	v_lshrrev_b32_e32 v44, 4, v51
	v_lshlrev_b32_e32 v44, 1, v44
	v_bfe_u32 v52, v156, 2, 1
	v_add_u32_e32 v44, v44, v52
	v_lshlrev_b32_e32 v44, 10, v44
	v_and_b32_e32 v52, 15, v51
	v_lshlrev_b32_e32 v52, 6, v52
	v_and_b32_e32 v53, 3, v156
	v_lshl_add_u32 v52, v53, 4, v52
	v_and_b32_e32 v53, 8, v51
	v_lshlrev_b32_e32 v53, 2, v53
	v_xor_b32_e32 v52, v52, v53
	v_add_u32_e32 v44, v44, v52
	v_add_u32_e32 v45, 0x2000, v44
	v_lshlrev_b32_e32 v50, 2, v40
	s_waitcnt lgkmcnt(0)
	s_cmpk_lt_i32 s24, 0x1340
	s_cbranch_scc0 .Lwt_down_p
	s_sub_i32 s25, s24, 0x840
	s_and_b32 s26, s25, 31
	s_lshr_b32 s27, s25, 5
	s_lshl_b32 s28, s26, 6
	s_and_b32 s29, s27, 1
	s_mul_i32 s29, s29, 0x1600
	s_lshr_b32 s30, s27, 1
	s_lshl_b32 s30, s30, 7
	s_add_i32 s29, s29, s30
	s_mul_i32 s30, s28, 0x2c00
	s_add_i32 s30, s30, s29
	s_lshl_b32 s30, s30, 2
	s_add_u32 s34, s18, s30
	s_addc_u32 s35, s19, 0
	s_lshl_b32 s31, s27, 5
	s_add_i32 s31, s31, s26
	s_mov_b32 s33, 0xb000
	s_mov_b32 s46, 1
	s_mov_b32 s30, 0x2100000
	s_branch .Lwt_dec_p
